# e33: as e32 but only two of each workgroup's three out_w/glu_w transpose items move to P3's pool workgroups; the third stays in P1
# speedup vs baseline: 1.0108x; 1.0030x over previous
; #define SUB(i, ...) do { if (PROBE_PH == phk && PROBE_SUB == (i)) { __syncthreads(); tp0 = __builtin_amdgcn_s_memrealtime(); } __VA_ARGS__ if (PROBE_PH == phk && PROBE_SUB == (i)) { asm volatile("s_waitcnt vmcnt(0)" ::: "memory"); __syncthreads(); tp1 = __builtin_amdgcn_s_memrealtime(); } } while (0)
; __global__ void __launch_bounds__(NTHREADS, 2) mk_fwd(Args a) {
;     ...
;         SUB(2, if (vcu < 128) transpose_dispatch((320 + vcu) * 8 + wave, a.in[7], a.in[20], a.in[18], a.in[8], a.ws, scr, lane);
;                else { const int b2 = vcu - 128;
;                    for (int it = 448 + 3 * b2; it < 448 + 3 * b2 + 3; ++it) transpose_dispatch(it * 8 + wave, a.in[7], a.in[20], a.in[18], a.in[8], a.ws, scr, lane);
;                    if (b2 < 16) transpose_dispatch((832 + b2) * 8 + wave, a.in[7], a.in[20], a.in[18], a.in[8], a.ws, scr, lane); } );
.Lp1_tr_setup:
	v_readlane_b32 s56, v254, 2
	v_and_b32_e32 v5, 7, v0
	v_readlane_b32 s70, v254, 16
	v_readlane_b32 s71, v254, 17
	v_mov_b32_e32 v7, 0
	s_add_u32 s10, s50, 0x1c00000
	v_lshlrev_b32_e32 v6, 4, v5
	s_mov_b64 s[22:23], s[70:71]
	s_addc_u32 s11, s51, 0
	v_lshl_add_u64 v[16:17], s[22:23], 0, v[6:7]
	s_mov_b64 s[8:9], 0x1000
	v_lshrrev_b32_e32 v24, 3, v212
	s_add_u32 s2, s50, 0x1400000
	v_lshl_add_u64 v[16:17], v[16:17], 0, s[8:9]
	v_lshl_add_u64 v[18:19], s[50:51], 0, v[6:7]
	s_mov_b64 s[8:9], 0x800000
	v_lshlrev_b32_e32 v4, 2, v5
	v_lshlrev_b32_e32 v2, 3, v5
	v_mul_u32_u24_e32 v5, 0x420, v5
	v_lshlrev_b32_e32 v12, 2, v24
	s_addc_u32 s3, s51, 0
	v_lshl_add_u64 v[18:19], v[18:19], 0, s[8:9]
	s_mul_i32 s9, s81, 24
	v_lshl_add_u64 v[8:9], s[40:41], 0, v[6:7]
	v_add_u32_e32 v26, s28, v6
	v_mul_u32_u24_e32 v27, 0x84, v24
	v_lshl_add_u64 v[10:11], s[10:11], 0, v[6:7]
	v_add3_u32 v5, s28, v5, v12
	v_lshl_add_u64 v[12:13], s[44:45], 0, v[6:7]
	v_lshl_add_u64 v[14:15], s[2:3], 0, v[6:7]
	v_lshlrev_b32_e32 v6, 6, v212
	s_add_i32 s12, s53, s9
	s_mul_i32 s7, s20, 3
	v_lshl_add_u64 v[20:21], s[22:23], 0, v[6:7]
	v_lshlrev_b32_e32 v6, 5, v212
	s_mul_i32 s8, s81, 3
	s_add_i32 s9, s12, 0xf380
	s_lshl_b32 s14, s12, 5
	s_addk_i32 s12, 0x180
	v_add_u32_e32 v26, v26, v27
	v_or_b32_e32 v25, 8, v24
	v_or_b32_e32 v3, 16, v24
	v_or_b32_e32 v1, 24, v24
	v_lshl_add_u64 v[22:23], s[4:5], 0, v[6:7]
	s_addk_i32 s7, 0x1c2
	s_add_i32 s8, s8, 63
	s_movk_i32 s18, 0x4000
	s_add_i32 s19, s14, 0x4000
	s_lshl_b32 s14, s12, 12
	s_lshl_b32 s12, s12, 14
	v_add_u32_e32 v27, 0x420, v26
	v_add_u32_e32 v28, 0x428, v26
	v_add_u32_e32 v29, 0x840, v26
	v_add_u32_e32 v30, 0x848, v26
	v_add_u32_e32 v31, 0xc60, v26
	v_add_u32_e32 v32, 0xc68, v26
	v_add_u32_e32 v33, 0x1080, v26
	v_add_u32_e32 v34, 0x1088, v26
	v_add_u32_e32 v35, 0x14a0, v26
	v_add_u32_e32 v36, 0x14a8, v26
	v_add_u32_e32 v37, 0x18c0, v26
	v_add_u32_e32 v38, 0x18c8, v26
	v_add_u32_e32 v39, 0x1ce0, v26
	v_add_u32_e32 v40, 0x1ce8, v26
	s_mov_b32 s29, 0x20000
	s_mov_b32 s30, 0x40000
	s_mov_b32 s31, 0x60000
	s_mov_b32 s33, 0x80000
	s_mov_b32 s34, 0xa0000
	s_mov_b32 s35, 0xc0000
	s_mov_b32 s36, 0xe0000
	s_mov_b64 s[22:23], 0x4000
	s_mov_b64 s[24:25], 0x8000
	s_mov_b32 s37, 0x8000
	s_mov_b64 s[26:27], 0xc000
	s_mov_b32 s54, 0xc000
	s_movk_i32 s55, 0x1000
	v_readlane_b32 s57, v254, 3
	v_readlane_b32 s58, v254, 4
	v_readlane_b32 s59, v254, 5
	v_readlane_b32 s60, v254, 6
	v_readlane_b32 s61, v254, 7
	v_readlane_b32 s62, v254, 8
	v_readlane_b32 s63, v254, 9
	v_readlane_b32 s64, v254, 10
	v_readlane_b32 s65, v254, 11
	v_readlane_b32 s66, v254, 12
	v_readlane_b32 s67, v254, 13
	v_readlane_b32 s68, v254, 14
	v_readlane_b32 s69, v254, 15
	s_cmp_eq_u32 s99, 1
	s_cbranch_scc1 .Lp3_tr_two
	s_cmpk_lt_i32 s81, 0x86
	s_cbranch_scc1 .LBB0_187
	s_add_i32 s8, s8, 2
	s_add_i32 s9, s9, 16
	s_addk_i32 s19, 0x200
	s_add_i32 s14, s14, 0x10000
	s_add_i32 s12, s12, 0x40000
	s_branch .LBB0_187
.Lp3_tr_two:
	s_sub_i32 s7, s7, 1
	s_branch .LBB0_187
